# v024: conv_item_p LayerNorm statistics reduced once per wave by lane pairs (same summation order) and broadcast with v_readlane instead of 64 redundant ds_read_b128 per lane; on top of v023
# speedup vs baseline: 1.0050x; 1.0050x over previous
.LBB0_433:
	s_or_b64 exec, exec, s[14:15]
	v_lshlrev_b32_e32 v81, 16, v81
	v_lshlrev_b32_e32 v122, 16, v54
	v_mul_f32_e32 v54, v165, v81
	v_fmac_f32_e32 v54, v163, v122
	s_waitcnt lgkmcnt(1)
	v_lshlrev_b32_e32 v121, 16, v121
	v_fmac_f32_e32 v54, v164, v121
	v_lshlrev_b32_e32 v105, 16, v105
	v_mul_f32_e32 v54, v54, v105
	v_lshlrev_b32_e32 v105, 16, v76
	v_mul_f32_e32 v76, v165, v122
	v_fmac_f32_e32 v76, v163, v105
	v_fmac_f32_e32 v76, v164, v81
	v_lshlrev_b32_e32 v81, 16, v120
	v_mul_f32_e32 v76, v76, v81
	v_lshlrev_b32_e32 v81, 16, v80
	v_mul_f32_e32 v80, v165, v105
	v_fmac_f32_e32 v80, v163, v81
	v_fmac_f32_e32 v80, v164, v122
	v_lshlrev_b32_e32 v119, 16, v119
	v_mul_f32_e32 v80, v80, v119
	v_lshlrev_b32_e32 v119, 16, v79
	v_mul_f32_e32 v79, v165, v81
	v_fmac_f32_e32 v79, v163, v119
	v_fmac_f32_e32 v79, v164, v105
	v_lshlrev_b32_e32 v105, 16, v118
	v_mul_f32_e32 v79, v79, v105
	v_lshlrev_b32_e32 v105, 16, v78
	v_mul_f32_e32 v78, v165, v119
	v_fmac_f32_e32 v78, v163, v105
	v_fmac_f32_e32 v78, v164, v81
	v_lshlrev_b32_e32 v81, 16, v117
	v_mul_f32_e32 v78, v78, v81
	v_lshlrev_b32_e32 v81, 16, v77
	v_mul_f32_e32 v77, v165, v105
	v_fmac_f32_e32 v77, v163, v81
	v_fmac_f32_e32 v77, v164, v119
	v_lshlrev_b32_e32 v116, 16, v116
	v_mul_f32_e32 v77, v77, v116
	v_lshlrev_b32_e32 v116, 16, v59
	v_mul_f32_e32 v59, v165, v81
	v_fmac_f32_e32 v59, v163, v116
	v_fmac_f32_e32 v59, v164, v105
	v_lshlrev_b32_e32 v105, 16, v115
	v_mul_f32_e32 v59, v59, v105
	v_lshlrev_b32_e32 v105, 16, v58
	v_mul_f32_e32 v58, v165, v116
	v_fmac_f32_e32 v58, v163, v105
	v_fmac_f32_e32 v58, v164, v81
	v_lshlrev_b32_e32 v81, 16, v114
	v_mul_f32_e32 v58, v58, v81
	v_lshlrev_b32_e32 v81, 16, v57
	v_mul_f32_e32 v57, v165, v105
	v_fmac_f32_e32 v57, v163, v81
	v_fmac_f32_e32 v57, v164, v116
	v_lshlrev_b32_e32 v113, 16, v113
	v_mul_f32_e32 v57, v57, v113
	v_lshlrev_b32_e32 v113, 16, v56
	v_mul_f32_e32 v56, v165, v81
	v_fmac_f32_e32 v56, v163, v113
	v_fmac_f32_e32 v56, v164, v105
	v_lshlrev_b32_e32 v105, 16, v112
	v_mul_f32_e32 v56, v56, v105
	v_lshlrev_b32_e32 v105, 16, v55
	v_mul_f32_e32 v55, v165, v113
	v_fmac_f32_e32 v55, v163, v105
	v_fmac_f32_e32 v55, v164, v81
	v_lshlrev_b32_e32 v81, 16, v111
	v_mul_f32_e32 v55, v55, v81
	v_lshlrev_b32_e32 v81, 16, v53
	v_mul_f32_e32 v53, v165, v105
	v_fmac_f32_e32 v53, v163, v81
	v_fmac_f32_e32 v53, v164, v113
	v_lshlrev_b32_e32 v110, 16, v110
	v_mul_f32_e32 v53, v53, v110
	v_lshlrev_b32_e32 v52, 16, v52
	v_mul_f32_e32 v110, v165, v81
	v_fmac_f32_e32 v110, v163, v52
	v_fmac_f32_e32 v110, v164, v105
	v_lshlrev_b32_e32 v105, 16, v109
	v_mul_f32_e32 v120, v110, v105
	v_lshlrev_b32_e32 v51, 16, v51
	v_mul_f32_e32 v105, v165, v52
	v_fmac_f32_e32 v105, v163, v51
	v_fmac_f32_e32 v105, v164, v81
	v_lshlrev_b32_e32 v81, 16, v108
	v_mul_f32_e32 v81, v105, v81
	v_lshlrev_b32_e32 v50, 16, v50
	v_mul_f32_e32 v105, v165, v51
	v_fmac_f32_e32 v105, v163, v50
	v_lshlrev_b32_e32 v104, 16, v104
	v_mul_f32_e32 v50, v165, v50
	v_fmac_f32_e32 v50, v163, v104
	v_fmac_f32_e32 v50, v164, v51
	v_lshlrev_b32_e32 v51, 16, v106
	v_readlane_b32 s15, v251, 9
	v_fmac_f32_e32 v105, v164, v52
	v_lshlrev_b32_e32 v52, 16, v107
	v_mul_f32_e32 v50, v50, v51
	v_mov_b32_e32 v51, s15
	s_add_i32 s30, 0, 0x22010
	v_mul_f32_e32 v52, v105, v52
	s_waitcnt lgkmcnt(0)
	s_barrier
	v_and_b32_e32 v104, 30, v64
	v_and_b32_e32 v105, 1, v64
	v_lshlrev_b32_e32 v104, 5, v104
	v_lshl_add_u32 v104, v105, 2, v104
	v_add_u32_e32 v104, 0x22000, v104
	ds_read2_b32 v[106:107], v104 offset1:2
	ds_read2_b32 v[108:109], v104 offset0:4 offset1:6
	ds_read2_b32 v[110:111], v104 offset0:8 offset1:10
	ds_read2_b32 v[112:113], v104 offset0:12 offset1:14
	v_cmp_eq_u32_e32 vcc, 1, v105
	s_mov_b32 s20, 0x3b000000
	s_waitcnt lgkmcnt(0)
	v_add_f32_e32 v106, v106, v107
	v_add_f32_e32 v108, v108, v109
	v_add_f32_e32 v106, v106, v108
	v_add_f32_e32 v110, v110, v111
	v_add_f32_e32 v106, v106, v110
	v_add_f32_e32 v112, v112, v113
	v_add_f32_e32 v106, v106, v112
	s_nop 1
	v_mov_b32_dpp v107, v106 quad_perm:[1,0,3,2] row_mask:0xf bank_mask:0xf
	v_cndmask_b32_e32 v212, v106, v107, vcc
	v_cndmask_b32_e32 v108, v107, v106, vcc
	v_mul_f32_e32 v109, 0x3b000000, v212
	v_mul_f32_e32 v109, v109, v109
	v_fma_f32 v108, v108, s20, -v109
	v_max_f32_e32 v108, 0, v108
	v_add_f32_e32 v108, 0x358637bd, v108
	v_rsq_f32_e32 v213, v108
	s_nop 1
	v_readlane_b32 s20, v212, 0
	v_readlane_b32 s21, v213, 0
	s_nop 1
	v_mov_b32_e32 v51, s30
	s_add_i32 s29, 0, 0x22020
	v_mov_b32_e32 v51, s29
	s_add_i32 s28, 0, 0x22030
	v_mov_b32_e32 v51, s28
	v_mov_b32_e32 v51, s20
	s_mov_b32 s16, 0x3b000000
	v_mov_b32_e32 v104, s21
	v_fmac_f32_e32 v49, 0xbb000000, v51
	v_cvt_pk_bf16_f32 v14, v14, s0
	ds_write_b16 v86, v14
	v_mul_f32_e32 v49, v49, v104
	v_fma_f32 v49, v143, v49, v142
	v_cvt_pk_bf16_f32 v14, v50, s0
	ds_write_b16 v86, v14 offset:16384
	v_mul_f32_e32 v14, 0xbfb8aa3b, v49
	v_exp_f32_e32 v14, v14
	v_readlane_b32 s15, v251, 10
	v_cvt_pk_bf16_f32 v15, v15, s0
	v_cvt_pk_bf16_f32 v12, v12, s0
	v_add_f32_e32 v14, 1.0, v14
	v_rcp_f32_e32 v14, v14
	v_cvt_pk_bf16_f32 v13, v13, s0
	v_cvt_pk_bf16_f32 v4, v4, s0
	v_cvt_pk_bf16_f32 v5, v5, s0
	v_mul_f32_e32 v14, v49, v14
	v_cvt_pk_bf16_f32 v14, v14, s0
	ds_write_b16 v86, v14 offset:32768
	v_mov_b32_e32 v14, s15
	v_readlane_b32 s15, v251, 17
	v_readlane_b32 s20, v212, 2
	v_readlane_b32 s21, v213, 2
	s_nop 1
	v_cvt_pk_bf16_f32 v0, v0, s0
	v_mov_b32_e32 v14, s15
	v_readlane_b32 s15, v251, 24
	v_cvt_pk_bf16_f32 v1, v1, s0
	v_mov_b32_e32 v14, s15
	v_readlane_b32 s15, v251, 31
	v_mov_b32_e32 v14, s15
	v_mov_b32_e32 v14, s20
	v_mov_b32_e32 v49, s21
	v_fmac_f32_e32 v47, 0xbb000000, v14
	ds_write_b16 v86, v15 offset:1024
	v_cvt_pk_bf16_f32 v15, v52, s0
	v_mul_f32_e32 v14, v47, v49
	v_fma_f32 v14, v143, v14, v142
	ds_write_b16 v86, v15 offset:17408
	v_mul_f32_e32 v15, 0xbfb8aa3b, v14
	v_exp_f32_e32 v15, v15
	v_readlane_b32 s15, v251, 11
	s_or_b32 s14, s33, s45
	v_lshlrev_b32_e32 v192, 1, v28
	v_add_f32_e32 v15, 1.0, v15
	v_rcp_f32_e32 v15, v15
	v_mov_b32_e32 v49, v193
	v_mul_f32_e32 v14, v14, v15
	v_cvt_pk_bf16_f32 v14, v14, s0
	ds_write_b16 v86, v14 offset:33792
	v_mov_b32_e32 v14, s15
	v_readlane_b32 s15, v251, 18
	v_readlane_b32 s20, v212, 4
	v_readlane_b32 s21, v213, 4
	s_nop 1
	s_nop 0
	v_mov_b32_e32 v14, s15
	v_readlane_b32 s15, v251, 25
	v_mov_b32_e32 v14, s15
	v_readlane_b32 s15, v251, 32
	v_mov_b32_e32 v14, s15
	v_mov_b32_e32 v14, s20
	v_mov_b32_e32 v15, s21
	v_fmac_f32_e32 v45, 0xbb000000, v14
	ds_write_b16 v86, v12 offset:2048
	v_cvt_pk_bf16_f32 v12, v81, s0
	v_mul_f32_e32 v14, v45, v15
	v_fma_f32 v14, v143, v14, v142
	ds_write_b16 v86, v12 offset:18432
	v_mul_f32_e32 v12, 0xbfb8aa3b, v14
	v_exp_f32_e32 v12, v12
	v_readlane_b32 s15, v251, 12
	v_mov_b32_e32 v45, v193
	v_mov_b32_e32 v47, v193
	v_add_f32_e32 v12, 1.0, v12
	v_rcp_f32_e32 v12, v12
	s_nop 0
	v_mul_f32_e32 v12, v14, v12
	v_cvt_pk_bf16_f32 v12, v12, s0
	ds_write_b16 v86, v12 offset:34816
	v_mov_b32_e32 v12, s15
	v_readlane_b32 s15, v251, 19
	v_readlane_b32 s20, v212, 6
	v_readlane_b32 s21, v213, 6
	s_nop 1
	s_nop 0
	v_mov_b32_e32 v12, s15
	v_readlane_b32 s15, v251, 26
	v_mov_b32_e32 v12, s15
	v_readlane_b32 s15, v251, 33
	v_mov_b32_e32 v12, s15
	v_mov_b32_e32 v12, s20
	v_mov_b32_e32 v14, s21
	v_fmac_f32_e32 v43, 0xbb000000, v12
	ds_write_b16 v86, v13 offset:3072
	v_cvt_pk_bf16_f32 v13, v120, s0
	v_mul_f32_e32 v12, v43, v14
	v_fma_f32 v12, v143, v12, v142
	ds_write_b16 v86, v13 offset:19456
	v_mul_f32_e32 v13, 0xbfb8aa3b, v12
	v_exp_f32_e32 v13, v13
	v_readlane_b32 s15, v251, 13
	v_add_f32_e32 v13, 1.0, v13
	v_rcp_f32_e32 v13, v13
	s_nop 0
	v_mul_f32_e32 v12, v12, v13
	v_cvt_pk_bf16_f32 v12, v12, s0
	ds_write_b16 v86, v12 offset:35840
	v_mov_b32_e32 v12, s15
	v_readlane_b32 s15, v251, 20
	v_readlane_b32 s20, v212, 8
	v_readlane_b32 s21, v213, 8
	s_nop 1
	s_nop 0
	v_mov_b32_e32 v43, s15
	v_readlane_b32 s15, v251, 27
	v_mov_b32_e32 v43, s15
	v_readlane_b32 s15, v251, 34
	v_mov_b32_e32 v43, s15
	v_mov_b32_e32 v12, s20
	v_mov_b32_e32 v13, s21
	v_fmac_f32_e32 v27, 0xbb000000, v12
	ds_write_b16 v86, v4 offset:4096
	v_cvt_pk_bf16_f32 v4, v53, s0
	v_mul_f32_e32 v12, v27, v13
	v_fma_f32 v12, v143, v12, v142
	ds_write_b16 v86, v4 offset:20480
	v_mul_f32_e32 v4, 0xbfb8aa3b, v12
	v_exp_f32_e32 v4, v4
	v_readlane_b32 s15, v251, 14
	v_mov_b32_e32 v43, v193
	v_add_f32_e32 v4, 1.0, v4
	v_rcp_f32_e32 v4, v4
	s_nop 0
	v_mul_f32_e32 v4, v12, v4
	v_cvt_pk_bf16_f32 v4, v4, s0
	ds_write_b16 v86, v4 offset:36864
	v_mov_b32_e32 v4, s15
	v_readlane_b32 s15, v251, 21
	v_readlane_b32 s20, v212, 10
	v_readlane_b32 s21, v213, 10
	s_nop 1
	s_nop 0
	v_mov_b32_e32 v4, s15
	v_readlane_b32 s15, v251, 28
	s_nop 0
	v_mov_b32_e32 v4, s15
	v_readlane_b32 s15, v251, 35
	s_nop 0
	v_mov_b32_e32 v4, s15
	v_mov_b32_e32 v4, s20
	v_mov_b32_e32 v12, s21
	v_fmac_f32_e32 v26, 0xbb000000, v4
	ds_write_b16 v86, v5 offset:5120
	v_cvt_pk_bf16_f32 v5, v55, s0
	v_mul_f32_e32 v4, v26, v12
	v_fma_f32 v4, v143, v4, v142
	ds_write_b16 v86, v5 offset:21504
	v_mul_f32_e32 v5, 0xbfb8aa3b, v4
	v_exp_f32_e32 v5, v5
	v_readlane_b32 s15, v251, 15
	v_add_f32_e32 v5, 1.0, v5
	v_rcp_f32_e32 v5, v5
	s_nop 0
	v_mul_f32_e32 v4, v4, v5
	v_cvt_pk_bf16_f32 v4, v4, s0
	ds_write_b16 v86, v4 offset:37888
	v_mov_b32_e32 v4, s15
	v_readlane_b32 s15, v251, 22
	v_readlane_b32 s20, v212, 12
	v_readlane_b32 s21, v213, 12
	s_nop 1
	s_nop 0
	v_mov_b32_e32 v4, s15
	v_readlane_b32 s15, v251, 29
	v_mov_b32_e32 v4, s15
	v_readlane_b32 s15, v251, 36
	s_nop 0
	v_mov_b32_e32 v4, s15
	v_mov_b32_e32 v4, s20
	v_mov_b32_e32 v5, s21
	v_fmac_f32_e32 v25, 0xbb000000, v4
	ds_write_b16 v86, v0 offset:6144
	v_cvt_pk_bf16_f32 v0, v56, s0
	v_mul_f32_e32 v4, v25, v5
	v_fma_f32 v4, v143, v4, v142
	ds_write_b16 v86, v0 offset:22528
	v_mul_f32_e32 v0, 0xbfb8aa3b, v4
	v_exp_f32_e32 v0, v0
	v_readlane_b32 s15, v251, 16
	v_add_f32_e32 v0, 1.0, v0
	v_rcp_f32_e32 v0, v0
	s_nop 0
	v_mul_f32_e32 v0, v4, v0
	v_cvt_pk_bf16_f32 v0, v0, s0
	ds_write_b16 v86, v0 offset:38912
	v_mov_b32_e32 v0, s15
	v_readlane_b32 s15, v251, 23
	v_readlane_b32 s20, v212, 14
	v_readlane_b32 s21, v213, 14
	s_nop 1
	s_nop 0
	v_mov_b32_e32 v0, s15
	v_readlane_b32 s15, v251, 30
	v_mov_b32_e32 v0, s15
	v_readlane_b32 s15, v251, 37
	v_mov_b32_e32 v0, s15
	v_mov_b32_e32 v0, s20
	v_mov_b32_e32 v4, s21
	v_fmac_f32_e32 v23, 0xbb000000, v0
	ds_write_b16 v86, v1 offset:7168
	v_cvt_pk_bf16_f32 v1, v57, s0
	v_mul_f32_e32 v0, v23, v4
	v_fma_f32 v0, v143, v0, v142
	ds_write_b16 v86, v1 offset:23552
	v_mul_f32_e32 v1, 0xbfb8aa3b, v0
	v_exp_f32_e32 v1, v1
	v_readlane_b32 s15, v252, 2
	v_add_f32_e32 v1, 1.0, v1
	v_rcp_f32_e32 v1, v1
	s_nop 0
	v_mul_f32_e32 v0, v0, v1
	v_cvt_pk_bf16_f32 v0, v0, s0
	ds_write_b16 v86, v0 offset:39936
	v_mov_b32_e32 v0, s15
	v_readlane_b32 s15, v252, 3
	v_readlane_b32 s20, v212, 16
	v_readlane_b32 s21, v213, 16
	s_nop 1
	s_nop 0
	v_mov_b32_e32 v0, s15
	v_readlane_b32 s15, v252, 4
	v_mov_b32_e32 v0, s15
	v_readlane_b32 s15, v252, 5
	v_mov_b32_e32 v0, s15
	v_mov_b32_e32 v0, s20
	v_mov_b32_e32 v1, s21
	v_fmac_f32_e32 v24, 0xbb000000, v0
	v_readlane_b32 s15, v252, 6
	v_mul_f32_e32 v0, v24, v1
	v_cvt_pk_bf16_f32 v1, v10, s0
	v_fma_f32 v0, v143, v0, v142
	ds_write_b16 v86, v1 offset:8192
	v_cvt_pk_bf16_f32 v1, v58, s0
	ds_write_b16 v86, v1 offset:24576
	v_mul_f32_e32 v1, 0xbfb8aa3b, v0
	v_exp_f32_e32 v1, v1
	s_nop 0
	v_add_f32_e32 v1, 1.0, v1
	v_rcp_f32_e32 v1, v1
	s_nop 0
	v_mul_f32_e32 v0, v0, v1
	v_cvt_pk_bf16_f32 v0, v0, s0
	ds_write_b16 v86, v0 offset:40960
	v_mov_b32_e32 v0, s15
	v_readlane_b32 s15, v252, 7
	v_readlane_b32 s20, v212, 18
	v_readlane_b32 s21, v213, 18
	s_nop 1
	s_nop 0
	v_mov_b32_e32 v0, s15
	v_readlane_b32 s15, v252, 8
	v_mov_b32_e32 v0, s15
	v_readlane_b32 s15, v252, 9
	v_mov_b32_e32 v0, s15
	v_mov_b32_e32 v0, s20
	v_mov_b32_e32 v1, s21
	v_fmac_f32_e32 v22, 0xbb000000, v0
	v_readlane_b32 s15, v252, 10
	v_mul_f32_e32 v0, v22, v1
	v_cvt_pk_bf16_f32 v1, v11, s0
	v_fma_f32 v0, v143, v0, v142
	ds_write_b16 v86, v1 offset:9216
	v_cvt_pk_bf16_f32 v1, v59, s0
	ds_write_b16 v86, v1 offset:25600
	v_mul_f32_e32 v1, 0xbfb8aa3b, v0
	v_exp_f32_e32 v1, v1
	s_nop 0
	v_add_f32_e32 v1, 1.0, v1
	v_rcp_f32_e32 v1, v1
	s_nop 0
	v_mul_f32_e32 v0, v0, v1
	v_cvt_pk_bf16_f32 v0, v0, s0
	ds_write_b16 v86, v0 offset:41984
	v_mov_b32_e32 v0, s15
	v_readlane_b32 s15, v252, 11
	v_readlane_b32 s20, v212, 20
	v_readlane_b32 s21, v213, 20
	s_nop 1
	s_nop 0
	v_mov_b32_e32 v0, s15
	v_readlane_b32 s15, v252, 12
	v_mov_b32_e32 v0, s15
	v_readlane_b32 s15, v252, 13
	v_mov_b32_e32 v0, s15
	v_mov_b32_e32 v0, s20
	v_mov_b32_e32 v1, s21
	v_fmac_f32_e32 v21, 0xbb000000, v0
	v_readlane_b32 s15, v252, 14
	v_mul_f32_e32 v0, v21, v1
	v_cvt_pk_bf16_f32 v1, v8, s0
	v_fma_f32 v0, v143, v0, v142
	ds_write_b16 v86, v1 offset:10240
	v_cvt_pk_bf16_f32 v1, v77, s0
	ds_write_b16 v86, v1 offset:26624
	v_mul_f32_e32 v1, 0xbfb8aa3b, v0
	v_exp_f32_e32 v1, v1
	s_nop 0
	v_add_f32_e32 v1, 1.0, v1
	v_rcp_f32_e32 v1, v1
	s_nop 0
	v_mul_f32_e32 v0, v0, v1
	v_cvt_pk_bf16_f32 v0, v0, s0
	ds_write_b16 v86, v0 offset:43008
	v_mov_b32_e32 v0, s15
	v_readlane_b32 s15, v252, 15
	v_readlane_b32 s20, v212, 22
	v_readlane_b32 s21, v213, 22
	s_nop 1
	s_nop 0
	v_mov_b32_e32 v0, s15
	v_readlane_b32 s15, v252, 16
	v_mov_b32_e32 v0, s15
	v_readlane_b32 s15, v252, 17
	v_mov_b32_e32 v0, s15
	v_mov_b32_e32 v0, s20
	v_mov_b32_e32 v1, s21
	v_fmac_f32_e32 v20, 0xbb000000, v0
	v_readlane_b32 s15, v252, 18
	v_mul_f32_e32 v0, v20, v1
	v_cvt_pk_bf16_f32 v1, v9, s0
	v_fma_f32 v0, v143, v0, v142
	ds_write_b16 v86, v1 offset:11264
	v_cvt_pk_bf16_f32 v1, v78, s0
	ds_write_b16 v86, v1 offset:27648
	v_mul_f32_e32 v1, 0xbfb8aa3b, v0
	v_exp_f32_e32 v1, v1
	s_nop 0
	v_add_f32_e32 v1, 1.0, v1
	v_rcp_f32_e32 v1, v1
	s_nop 0
	v_mul_f32_e32 v0, v0, v1
	v_cvt_pk_bf16_f32 v0, v0, s0
	ds_write_b16 v86, v0 offset:44032
	v_mov_b32_e32 v0, s15
	v_readlane_b32 s15, v252, 19
	v_readlane_b32 s20, v212, 24
	v_readlane_b32 s21, v213, 24
	s_nop 1
	s_nop 0
	v_mov_b32_e32 v0, s15
	v_readlane_b32 s15, v252, 20
	v_mov_b32_e32 v0, s15
	v_readlane_b32 s15, v252, 21
	v_mov_b32_e32 v0, s15
	v_mov_b32_e32 v0, s20
	v_mov_b32_e32 v1, s21
	v_fmac_f32_e32 v19, 0xbb000000, v0
	v_readlane_b32 s15, v252, 22
	v_mul_f32_e32 v0, v19, v1
	v_cvt_pk_bf16_f32 v1, v2, s0
	v_fma_f32 v0, v143, v0, v142
	ds_write_b16 v86, v1 offset:12288
	v_cvt_pk_bf16_f32 v1, v79, s0
	ds_write_b16 v86, v1 offset:28672
	v_mul_f32_e32 v1, 0xbfb8aa3b, v0
	v_exp_f32_e32 v1, v1
	s_nop 0
	v_add_f32_e32 v1, 1.0, v1
	v_rcp_f32_e32 v1, v1
	s_nop 0
	v_mul_f32_e32 v0, v0, v1
	v_cvt_pk_bf16_f32 v0, v0, s0
	ds_write_b16 v86, v0 offset:45056
	v_mov_b32_e32 v0, s15
	v_readlane_b32 s15, v252, 23
	v_readlane_b32 s20, v212, 26
	v_readlane_b32 s21, v213, 26
	s_nop 1
	s_nop 0
	v_mov_b32_e32 v0, s15
	v_readlane_b32 s15, v252, 24
	v_mov_b32_e32 v0, s15
	v_readlane_b32 s15, v252, 25
	v_mov_b32_e32 v0, s15
	v_mov_b32_e32 v0, s20
	v_mov_b32_e32 v1, s21
	v_fmac_f32_e32 v18, 0xbb000000, v0
	v_readlane_b32 s15, v252, 26
	v_mul_f32_e32 v0, v18, v1
	v_cvt_pk_bf16_f32 v1, v3, s0
	v_fma_f32 v0, v143, v0, v142
	ds_write_b16 v86, v1 offset:13312
	v_cvt_pk_bf16_f32 v1, v80, s0
	ds_write_b16 v86, v1 offset:29696
	v_mul_f32_e32 v1, 0xbfb8aa3b, v0
	v_exp_f32_e32 v1, v1
	s_nop 0
	v_add_f32_e32 v1, 1.0, v1
	v_rcp_f32_e32 v1, v1
	s_nop 0
	v_mul_f32_e32 v0, v0, v1
	v_cvt_pk_bf16_f32 v0, v0, s0
	ds_write_b16 v86, v0 offset:46080
	v_mov_b32_e32 v0, s15
	v_readlane_b32 s15, v252, 27
	v_readlane_b32 s20, v212, 28
	v_readlane_b32 s21, v213, 28
	s_nop 1
	s_nop 0
	v_mov_b32_e32 v4, s15
	v_readlane_b32 s15, v252, 28
	v_mov_b32_e32 v4, s15
	v_readlane_b32 s15, v252, 29
	v_mov_b32_e32 v4, s15
	v_mov_b32_e32 v0, s20
	v_mov_b32_e32 v1, s21
	v_fmac_f32_e32 v17, 0xbb000000, v0
	v_readlane_b32 s15, v252, 30
	v_mul_f32_e32 v0, v17, v1
	v_cvt_pk_bf16_f32 v1, v6, s0
	v_fma_f32 v0, v143, v0, v142
	ds_write_b16 v86, v1 offset:14336
	v_cvt_pk_bf16_f32 v1, v76, s0
	ds_write_b16 v86, v1 offset:30720
	v_mul_f32_e32 v1, 0xbfb8aa3b, v0
	v_exp_f32_e32 v1, v1
	s_nop 0
	v_add_f32_e32 v1, 1.0, v1
	v_rcp_f32_e32 v1, v1
	s_nop 0
	v_mul_f32_e32 v0, v0, v1
	v_cvt_pk_bf16_f32 v0, v0, s0
	ds_write_b16 v86, v0 offset:47104
	v_mov_b32_e32 v0, s15
	v_readlane_b32 s15, v252, 31
	v_readlane_b32 s20, v212, 30
	v_readlane_b32 s21, v213, 30
	s_nop 1
	s_nop 0
	v_mov_b32_e32 v4, s15
	v_readlane_b32 s15, v252, 32
	v_mov_b32_e32 v4, s15
	v_readlane_b32 s15, v252, 33
	v_mov_b32_e32 v4, s15
	v_mov_b32_e32 v0, s20
	v_mov_b32_e32 v1, s21
	v_fmac_f32_e32 v16, 0xbb000000, v0
	s_ashr_i32 s15, s14, 31
	s_mov_b64 s[16:17], s[42:43]
	v_mul_f32_e32 v0, v16, v1
	v_cvt_pk_bf16_f32 v1, v7, s0
	v_fma_f32 v0, v143, v0, v142
	ds_write_b16 v86, v1 offset:15360
	v_cvt_pk_bf16_f32 v1, v54, s0
	ds_write_b16 v86, v1 offset:31744
	v_mul_f32_e32 v1, 0xbfb8aa3b, v0
	v_exp_f32_e32 v1, v1
	s_lshl_b64 s[14:15], s[14:15], 12
	v_add_f32_e32 v1, 1.0, v1
	v_rcp_f32_e32 v1, v1
	s_nop 0
	v_mul_f32_e32 v0, v0, v1
	v_cvt_pk_bf16_f32 v0, v0, s0
	ds_write_b16 v86, v0 offset:48128
	s_waitcnt lgkmcnt(0)
	s_barrier
	s_add_u32 s14, s16, s14
	s_addc_u32 s15, s17, s15
	s_add_u32 s14, s14, 0x14000000
	ds_read_b128 v[0:3], v92
	s_addc_u32 s15, s15, 0
	v_lshl_add_u64 v[4:5], s[14:15], 0, v[42:43]
	v_lshl_add_u64 v[6:7], v[30:31], 1, v[4:5]
	v_lshl_add_u64 v[6:7], v[6:7], 0, v[192:193]
	s_waitcnt lgkmcnt(0)
	global_store_dwordx4 v[6:7], v[0:3], off
	ds_read_b128 v[0:3], v93
	v_lshl_add_u64 v[6:7], s[14:15], 0, v[44:45]
	v_lshl_add_u64 v[6:7], v[32:33], 1, v[6:7]
	v_lshl_add_u64 v[6:7], v[6:7], 0, v[192:193]
	s_add_i32 s54, s54, 1
	s_waitcnt lgkmcnt(0)
	global_store_dwordx4 v[6:7], v[0:3], off
	ds_read_b128 v[0:3], v94
	v_lshl_add_u64 v[6:7], v[34:35], 1, v[4:5]
	v_lshl_add_u64 v[6:7], v[6:7], 0, v[192:193]
	v_lshl_add_u64 v[4:5], v[38:39], 1, v[4:5]
	v_lshl_add_u64 v[4:5], v[4:5], 0, v[192:193]
	s_waitcnt lgkmcnt(0)
	global_store_dwordx4 v[6:7], v[0:3], off
	ds_read_b128 v[0:3], v95
	v_lshl_add_u64 v[6:7], s[14:15], 0, v[46:47]
	v_lshl_add_u64 v[6:7], v[36:37], 1, v[6:7]
	v_lshl_add_u64 v[6:7], v[6:7], 0, v[192:193]
	s_cmp_eq_u32 s54, 4
	s_waitcnt lgkmcnt(0)
	global_store_dwordx4 v[6:7], v[0:3], off
	ds_read_b128 v[0:3], v96
	s_waitcnt lgkmcnt(0)
	global_store_dwordx4 v[4:5], v[0:3], off
	ds_read_b128 v[0:3], v97
	v_lshl_add_u64 v[4:5], s[14:15], 0, v[48:49]
	v_lshl_add_u64 v[4:5], v[40:41], 1, v[4:5]
	v_lshl_add_u64 v[4:5], v[4:5], 0, v[192:193]
	s_waitcnt lgkmcnt(0)
	global_store_dwordx4 v[4:5], v[0:3], off
	s_waitcnt lgkmcnt(0)
	s_barrier
	s_cbranch_scc1 .LBB0_569
